# IN sample rows as 256 skinny units (16 rows x 128 cols each, operands loaded straight into MFMA fragments, no LDS) spread over all blocks instead of 16 full tiles on 16 blocks
# speedup vs baseline: 1.0040x; 1.0040x over previous
; DI void gemm_stream2(const bf16_t* __restrict__ A, int lda, const bf16_t* __restrict__ Bt, int ldb, int K, int m0, int n0, ...
;     ...
;             for (int mi = 0; mi < 4; ++mi)
; #pragma unroll
;                 for (int ni = 0; ni < 4; ++ni) acc[mi][ni] = __builtin_amdgcn_mfma_f32_16x16x32_bf16(bfr[ni], af[mi], acc[mi][ni], 0, 0, 0);
; DI void gemm_in(const Params& p, int l, int bid, int nb, char* smem, const int tid) {
;     ...
;     for (; have; tm = tm2, tn = tn2) {
;         have = ti.next(tm2, tn2);
;         const int m0 = tm * 256, n0 = tn * 128;
;         f32x4 acc[4][4]; zero_acc(acc);
;         gemm_stream(A, 1024, Bt, 1024, 1024, m0, n0, have, tm2 * 256, tn2 * 128, smem, acc, tid, rg);
.Lin_stub:
	s_waitcnt vmcnt(0) lgkmcnt(0)
	v_readlane_b32 s55, v240, 0
	v_readlane_b32 s53, v238, 54
	v_readfirstlane_b32 s10, v193
	s_nop 3
	s_lshr_b32 s10, s10, 6
	s_cmpk_lt_u32 s55, 0x100
	s_cbranch_scc0 .LBB0_860
	v_and_b32_e32 v190, 63, v193
	v_and_b32_e32 v191, 15, v190
	v_lshrrev_b32_e32 v17, 4, v190
	v_lshlrev_b32_e32 v186, 4, v17
	v_lshl_add_u32 v186, v191, 11, v186
.Lin_su:
	s_lshr_b32 s93, s55, 4
	s_and_b32 s98, s55, 15
	s_lshl_b32 s1, s93, 15
	s_add_u32 s1, s1, 0x5240000
	s_add_u32 s66, s88, s1
	s_addc_u32 s67, s89, 0
	s_lshl_b32 s1, s98, 18
	s_lshl_b32 s2, s10, 15
	s_add_u32 s1, s1, s2
	s_add_u32 s1, s1, 0x1080000
	s_add_u32 s70, s88, s1
	s_addc_u32 s71, s89, 0
	global_load_dwordx4 v[28:31], v186, s[66:67] offset:0
	global_load_dwordx4 v[92:95], v186, s[70:71] offset:0
	global_load_dwordx4 v[32:35], v186, s[66:67] offset:64
	global_load_dwordx4 v[96:99], v186, s[70:71] offset:64
	global_load_dwordx4 v[36:39], v186, s[66:67] offset:128
	global_load_dwordx4 v[100:103], v186, s[70:71] offset:128
	global_load_dwordx4 v[40:43], v186, s[66:67] offset:192
	global_load_dwordx4 v[104:107], v186, s[70:71] offset:192
	global_load_dwordx4 v[44:47], v186, s[66:67] offset:256
	global_load_dwordx4 v[108:111], v186, s[70:71] offset:256
	global_load_dwordx4 v[48:51], v186, s[66:67] offset:320
	global_load_dwordx4 v[112:115], v186, s[70:71] offset:320
	global_load_dwordx4 v[52:55], v186, s[66:67] offset:384
	global_load_dwordx4 v[116:119], v186, s[70:71] offset:384
	global_load_dwordx4 v[56:59], v186, s[66:67] offset:448
	global_load_dwordx4 v[120:123], v186, s[70:71] offset:448
	global_load_dwordx4 v[60:63], v186, s[66:67] offset:512
	global_load_dwordx4 v[124:127], v186, s[70:71] offset:512
	global_load_dwordx4 v[64:67], v186, s[66:67] offset:576
	global_load_dwordx4 v[128:131], v186, s[70:71] offset:576
	global_load_dwordx4 v[68:71], v186, s[66:67] offset:640
	global_load_dwordx4 v[132:135], v186, s[70:71] offset:640
	global_load_dwordx4 v[72:75], v186, s[66:67] offset:704
	global_load_dwordx4 v[136:139], v186, s[70:71] offset:704
	global_load_dwordx4 v[76:79], v186, s[66:67] offset:768
	global_load_dwordx4 v[140:143], v186, s[70:71] offset:768
	global_load_dwordx4 v[80:83], v186, s[66:67] offset:832
	global_load_dwordx4 v[144:147], v186, s[70:71] offset:832
	global_load_dwordx4 v[84:87], v186, s[66:67] offset:896
	global_load_dwordx4 v[148:151], v186, s[70:71] offset:896
	global_load_dwordx4 v[88:91], v186, s[66:67] offset:960
	global_load_dwordx4 v[152:155], v186, s[70:71] offset:960
	v_mov_b64_e32 v[24:25], 0
	v_mov_b64_e32 v[26:27], 0
	s_waitcnt vmcnt(30)
	v_mfma_f32_16x16x32_bf16 v[24:27], v[92:95], v[28:31], v[24:27]
	global_load_dwordx4 v[28:31], v186, s[66:67] offset:1024
	global_load_dwordx4 v[92:95], v186, s[70:71] offset:1024
	s_waitcnt vmcnt(30)
	v_mfma_f32_16x16x32_bf16 v[24:27], v[96:99], v[32:35], v[24:27]
	global_load_dwordx4 v[32:35], v186, s[66:67] offset:1088
	global_load_dwordx4 v[96:99], v186, s[70:71] offset:1088
	s_waitcnt vmcnt(30)
	v_mfma_f32_16x16x32_bf16 v[24:27], v[100:103], v[36:39], v[24:27]
	global_load_dwordx4 v[36:39], v186, s[66:67] offset:1152
	global_load_dwordx4 v[100:103], v186, s[70:71] offset:1152
	s_waitcnt vmcnt(30)
	v_mfma_f32_16x16x32_bf16 v[24:27], v[104:107], v[40:43], v[24:27]
	global_load_dwordx4 v[40:43], v186, s[66:67] offset:1216
	global_load_dwordx4 v[104:107], v186, s[70:71] offset:1216
	s_waitcnt vmcnt(30)
	v_mfma_f32_16x16x32_bf16 v[24:27], v[108:111], v[44:47], v[24:27]
	global_load_dwordx4 v[44:47], v186, s[66:67] offset:1280
	global_load_dwordx4 v[108:111], v186, s[70:71] offset:1280
	s_waitcnt vmcnt(30)
	v_mfma_f32_16x16x32_bf16 v[24:27], v[112:115], v[48:51], v[24:27]
	global_load_dwordx4 v[48:51], v186, s[66:67] offset:1344
	global_load_dwordx4 v[112:115], v186, s[70:71] offset:1344
	s_waitcnt vmcnt(30)
	v_mfma_f32_16x16x32_bf16 v[24:27], v[116:119], v[52:55], v[24:27]
	global_load_dwordx4 v[52:55], v186, s[66:67] offset:1408
	global_load_dwordx4 v[116:119], v186, s[70:71] offset:1408
	s_waitcnt vmcnt(30)
	v_mfma_f32_16x16x32_bf16 v[24:27], v[120:123], v[56:59], v[24:27]
	global_load_dwordx4 v[56:59], v186, s[66:67] offset:1472
	global_load_dwordx4 v[120:123], v186, s[70:71] offset:1472
	s_waitcnt vmcnt(30)
	v_mfma_f32_16x16x32_bf16 v[24:27], v[124:127], v[60:63], v[24:27]
	global_load_dwordx4 v[60:63], v186, s[66:67] offset:1536
	global_load_dwordx4 v[124:127], v186, s[70:71] offset:1536
	s_waitcnt vmcnt(30)
	v_mfma_f32_16x16x32_bf16 v[24:27], v[128:131], v[64:67], v[24:27]
	global_load_dwordx4 v[64:67], v186, s[66:67] offset:1600
	global_load_dwordx4 v[128:131], v186, s[70:71] offset:1600
	s_waitcnt vmcnt(30)
	v_mfma_f32_16x16x32_bf16 v[24:27], v[132:135], v[68:71], v[24:27]
	global_load_dwordx4 v[68:71], v186, s[66:67] offset:1664
	global_load_dwordx4 v[132:135], v186, s[70:71] offset:1664
	s_waitcnt vmcnt(30)
; DI unsigned pk2(float lo, float hi) { const f32x2 v = {lo, hi}; return __builtin_bit_cast(unsigned, __builtin_convertvector(v, bf2_t)); }
; DI void gemm_in(const Params& p, int l, int bid, int nb, char* smem, const int tid) {
;     ...
;         const int nb0 = n0 + wn * 64;
;         const int seg = nb0 >> 8;
;         const int cin = nb0 & 255;
;         if (seg == 0 || seg == 3) {
;             bf16_t* Q = (bf16_t*)(p.ws + (seg == 0 ? B_QA : B_QC));
; #pragma unroll
;             for (int mi = 0; mi < 4; ++mi) {
;                 const int row = m0 + wm * 64 + mi * 16 + r;
; #pragma unroll
;                 for (int ni = 0; ni < 4; ++ni) {
;                     u32x2 w; w.x = pk2(acc[mi][ni][0], acc[mi][ni][1]); w.y = pk2(acc[mi][ni][2], acc[mi][ni][3]);
;                     *(u32x2*)(Q + (size_t)row * 256 + cin + ni * 16 + q * 4) = w;
;                 }
;             }
;         } else if (seg < 6) {
;             const size_t boff = seg == 1 ? B_KA : seg == 2 ? B_VA : seg == 4 ? B_KC : B_VC;
;             const bool samp = m0 >= NP;
;             const size_t ooff = samp ? (seg == 1 ? O_AKS : seg == 2 ? O_AVS : seg == 4 ? O_CKS : O_CVS) : (seg == 1 ? O_AKP : seg == 2 ? O_AVP : seg == 4 ? O_CKP : O_CVP);
;             bf16_t* KV = (bf16_t*)(p.ws + boff);
; #pragma unroll
;             for (int mi = 0; mi < 4; ++mi) {
;                 const int row = m0 + wm * 64 + mi * 16 + r;
;                 const size_t srow = samp ? (size_t)(l * NS + (row - NP)) : (size_t)(l * NP + row);
;                 const size_t kr = (size_t)krow_of(row);
; #pragma unroll
;                 for (int ni = 0; ni < 4; ++ni) {
;                     const int c = cin + ni * 16 + q * 4;
;                     *(f32x4*)(p.out + ooff + srow * 256 + c) = acc[mi][ni];
;                     u32x2 w; w.x = pk2(acc[mi][ni][0], acc[mi][ni][1]); w.y = pk2(acc[mi][ni][2], acc[mi][ni][3]);
;                     *(u32x2*)(KV + kr * 256 + c) = w;
;                 }
;             }
;         } else {
;             float* SM = (float*)(p.ws + B_SMALL);
; #pragma unroll
;             for (int mi = 0; mi < 4; ++mi) {
;                 const int row = m0 + wm * 64 + mi * 16 + r;
; #pragma unroll
;                 for (int ni = 0; ni < 4; ++ni) *(f32x4*)(SM + (size_t)row * 512 + (nb0 - 1536) + ni * 16 + q * 4) = acc[mi][ni];
;             }
;         }
	v_mfma_f32_16x16x32_bf16 v[24:27], v[136:139], v[72:75], v[24:27]
	global_load_dwordx4 v[72:75], v186, s[66:67] offset:1728
	global_load_dwordx4 v[136:139], v186, s[70:71] offset:1728
	s_waitcnt vmcnt(30)
	v_mfma_f32_16x16x32_bf16 v[24:27], v[140:143], v[76:79], v[24:27]
	global_load_dwordx4 v[76:79], v186, s[66:67] offset:1792
	global_load_dwordx4 v[140:143], v186, s[70:71] offset:1792
	s_waitcnt vmcnt(30)
	v_mfma_f32_16x16x32_bf16 v[24:27], v[144:147], v[80:83], v[24:27]
	global_load_dwordx4 v[80:83], v186, s[66:67] offset:1856
	global_load_dwordx4 v[144:147], v186, s[70:71] offset:1856
	s_waitcnt vmcnt(30)
	v_mfma_f32_16x16x32_bf16 v[24:27], v[148:151], v[84:87], v[24:27]
	global_load_dwordx4 v[84:87], v186, s[66:67] offset:1920
	global_load_dwordx4 v[148:151], v186, s[70:71] offset:1920
	s_waitcnt vmcnt(30)
	v_mfma_f32_16x16x32_bf16 v[24:27], v[152:155], v[88:91], v[24:27]
	global_load_dwordx4 v[88:91], v186, s[66:67] offset:1984
	global_load_dwordx4 v[152:155], v186, s[70:71] offset:1984
	s_waitcnt vmcnt(30)
	v_mfma_f32_16x16x32_bf16 v[24:27], v[92:95], v[28:31], v[24:27]
	s_waitcnt vmcnt(28)
	v_mfma_f32_16x16x32_bf16 v[24:27], v[96:99], v[32:35], v[24:27]
	s_waitcnt vmcnt(26)
	v_mfma_f32_16x16x32_bf16 v[24:27], v[100:103], v[36:39], v[24:27]
	s_waitcnt vmcnt(24)
	v_mfma_f32_16x16x32_bf16 v[24:27], v[104:107], v[40:43], v[24:27]
	s_waitcnt vmcnt(22)
	v_mfma_f32_16x16x32_bf16 v[24:27], v[108:111], v[44:47], v[24:27]
	s_waitcnt vmcnt(20)
	v_mfma_f32_16x16x32_bf16 v[24:27], v[112:115], v[48:51], v[24:27]
	s_waitcnt vmcnt(18)
	v_mfma_f32_16x16x32_bf16 v[24:27], v[116:119], v[52:55], v[24:27]
	s_waitcnt vmcnt(16)
	v_mfma_f32_16x16x32_bf16 v[24:27], v[120:123], v[56:59], v[24:27]
	s_waitcnt vmcnt(14)
	v_mfma_f32_16x16x32_bf16 v[24:27], v[124:127], v[60:63], v[24:27]
	s_waitcnt vmcnt(12)
	v_mfma_f32_16x16x32_bf16 v[24:27], v[128:131], v[64:67], v[24:27]
	s_waitcnt vmcnt(10)
	v_mfma_f32_16x16x32_bf16 v[24:27], v[132:135], v[68:71], v[24:27]
	s_waitcnt vmcnt(8)
	v_mfma_f32_16x16x32_bf16 v[24:27], v[136:139], v[72:75], v[24:27]
	s_waitcnt vmcnt(6)
	v_mfma_f32_16x16x32_bf16 v[24:27], v[140:143], v[76:79], v[24:27]
	s_waitcnt vmcnt(4)
	v_mfma_f32_16x16x32_bf16 v[24:27], v[144:147], v[80:83], v[24:27]
	s_waitcnt vmcnt(2)
	v_mfma_f32_16x16x32_bf16 v[24:27], v[148:151], v[84:87], v[24:27]
	s_waitcnt vmcnt(0)
	v_mfma_f32_16x16x32_bf16 v[24:27], v[152:155], v[88:91], v[24:27]
	s_lshr_b32 s37, s98, 1
	s_and_b32 s62, s98, 1
	s_lshl_b32 s62, s62, 7
	s_lshl_b32 s1, s10, 4
	s_add_u32 s62, s62, s1
	v_lshlrev_b32_e32 v187, 3, v17
	v_lshl_add_u32 v188, v191, 9, v187
	v_lshlrev_b32_e32 v189, 1, v187
	s_nop 7
	s_nop 7
	s_cmp_eq_u32 s37, 0
	s_cbranch_scc1 .Lin_su_q
	s_cmp_eq_u32 s37, 3
	s_cbranch_scc1 .Lin_su_q
	s_cmp_ge_u32 s37, 6
	s_cbranch_scc1 .Lin_su_sm
	s_mov_b32 s1, 0xd750000
	s_mov_b32 s2, 0x9fc0000
	s_cmp_eq_u32 s37, 4
	s_cselect_b32 s1, 0xd6d0000, s1
	s_cselect_b32 s2, 0x93a0000, s2
	s_cmp_eq_u32 s37, 2
	s_cselect_b32 s1, 0xd600000, s1
	s_cselect_b32 s2, 0x8780000, s2
	s_cmp_eq_u32 s37, 1
	s_cselect_b32 s1, 0xd580000, s1
	s_cselect_b32 s2, 0x7b60000, s2
	v_readlane_b32 s3, v231, 4
	s_lshl_b32 s3, s3, 18
	s_add_u32 s1, s1, s3
	s_lshl_b32 s3, s93, 14
	s_add_u32 s1, s1, s3
	s_lshl_b32 s3, s62, 2
	s_add_u32 s1, s1, s3
	v_readlane_b32 s74, v240, 5
	v_readlane_b32 s75, v240, 6
	s_nop 3
	s_add_u32 s74, s74, s1
	s_addc_u32 s75, s75, 0
	v_lshl_add_u32 v187, v191, 10, v189
	global_store_dwordx4 v187, v[24:27], s[74:75]
	s_lshr_b32 s1, s93, 1
	s_mul_i32 s1, s1, 0x420
	s_and_b32 s3, s93, 1
	s_lshl_b32 s3, s3, 4
	s_add_u32 s1, s1, s3
	s_add_u32 s1, s1, 0x4400
	s_lshl_b32 s1, s1, 9
	s_add_u32 s1, s1, s2
	s_lshl_b32 s3, s62, 1
	s_add_u32 s1, s1, s3
	s_add_u32 s80, s88, s1
	s_addc_u32 s81, s89, 0
	v_cvt_pk_bf16_f32 v28, v24, v25
	v_cvt_pk_bf16_f32 v29, v26, v27
	global_store_dwordx2 v188, v[28:29], s[80:81]
	s_branch .Lin_su_done
.Lin_su_q:
	s_mov_b32 s2, 0x5ae0000
	s_cmp_eq_u32 s37, 0
	s_cselect_b32 s2, 0x52c0000, s2
	s_lshl_b32 s1, s93, 13
	s_add_u32 s1, s1, 0x800000
	s_add_u32 s1, s1, s2
	s_lshl_b32 s3, s62, 1
	s_add_u32 s1, s1, s3
	s_add_u32 s80, s88, s1
	s_addc_u32 s81, s89, 0
	v_cvt_pk_bf16_f32 v28, v24, v25
	v_cvt_pk_bf16_f32 v29, v26, v27
	global_store_dwordx2 v188, v[28:29], s[80:81]
	s_branch .Lin_su_done
.Lin_su_sm:
	s_sub_u32 s1, s37, 6
	s_lshl_b32 s1, s1, 8
	s_add_u32 s1, s1, s62
	s_lshl_b32 s1, s1, 2
	s_lshl_b32 s3, s93, 15
	s_add_u32 s1, s1, s3
	s_add_u32 s1, s1, 0xcc20000
	s_add_u32 s80, s88, s1
	s_addc_u32 s81, s89, 0
	v_lshl_add_u32 v187, v191, 11, v189
	global_store_dwordx4 v187, v[24:27], s[80:81]
.Lin_su_done:
	s_add_u32 s55, s55, s53
	s_cmpk_lt_u32 s55, 0x100
	s_cbranch_scc1 .Lin_su
	s_branch .LBB0_860
